# rowpass DPP wave-sum pads shrunk from two wait states to one where the other row's DPP supplies the second
# baseline (speedup 1.0000x reference)
; DI float bflo(unsigned u) { return __uint_as_float(u << 16); }
; DI float bfhi(unsigned u) { return __uint_as_float(u & 0xffff0000u); }
; DI void rowpass(const float* hsrc, const bf16_t* mix, const float* gpost, const float* gnext, float* hdst, bf16_t* hb, int gw, int NGW, int lane) {
;     ...
;         if (mix) {
; #pragma unroll
;             for (int r = 0; r < 2; ++r)
; #pragma unroll
;                 for (int j = 0; j < 4; ++j) { const u32x2 w = __builtin_nontemporal_load((const u32x2*)(mix + (size_t)(m0 + r) * D + 256 * j + 4 * lane)); mv[r][j] = (f32x4){bflo(w.x), bfhi(w.x), bflo(w.y), bfhi(w.y)}; }
;             float ss[2] = {0.f, 0.f};
; #pragma unroll
;             for (int r = 0; r < 2; ++r)
; #pragma unroll
;                 for (int j = 0; j < 4; ++j) ss[r] += (mv[r][j].x * mv[r][j].x + mv[r][j].y * mv[r][j].y) + (mv[r][j].z * mv[r][j].z + mv[r][j].w * mv[r][j].w);
; #pragma unroll
;             for (int o = 1; o < 64; o <<= 1) { ss[0] += __shfl_xor(ss[0], o); ss[1] += __shfl_xor(ss[1], o); }
; #pragma unroll
;             for (int r = 0; r < 2; ++r) { const float rs = __builtin_amdgcn_rsqf(ss[r] * (1.0f / D) + EPS);
; #pragma unroll
;                 for (int j = 0; j < 4; ++j) { const f32x4 gp = *(const f32x4*)(gpost + 256 * j + 4 * lane); hv[r][j] += mv[r][j] * rs * gp; *(f32x4*)(hdst + (size_t)(m0 + r) * D + 256 * j + 4 * lane) = hv[r][j]; } }
.LBB0_401:
	global_load_dwordx2 v[0:1], v[36:37], off offset:0 nt
	global_load_dwordx2 v[2:3], v[36:37], off offset:512 nt
	global_load_dwordx2 v[4:5], v[36:37], off offset:1024 nt
	global_load_dwordx2 v[6:7], v[36:37], off offset:1536 nt
	global_load_dwordx2 v[8:9], v[36:37], off offset:2048 nt
	global_load_dwordx2 v[10:11], v[36:37], off offset:2560 nt
	global_load_dwordx2 v[12:13], v[36:37], off offset:3072 nt
	global_load_dwordx2 v[14:15], v[36:37], off offset:3584 nt
	global_load_dwordx4 v[88:91], v80, s[30:31] offset:0 nt
	global_load_dwordx4 v[92:95], v80, s[30:31] offset:1024 nt
	global_load_dwordx4 v[96:99], v80, s[30:31] offset:2048 nt
	global_load_dwordx4 v[100:103], v80, s[30:31] offset:3072 nt
	global_load_dwordx4 v[104:107], v86, s[30:31] offset:0 nt
	global_load_dwordx4 v[108:111], v86, s[30:31] offset:1024 nt
	global_load_dwordx4 v[112:115], v86, s[30:31] offset:2048 nt
	global_load_dwordx4 v[116:119], v86, s[30:31] offset:3072 nt
	s_waitcnt vmcnt(8)
	v_lshlrev_b32_e32 v48, 16, v0
	v_and_b32_e32 v49, 0xffff0000, v0
	v_lshlrev_b32_e32 v50, 16, v1
	v_and_b32_e32 v51, 0xffff0000, v1
	v_lshlrev_b32_e32 v52, 16, v2
	v_and_b32_e32 v53, 0xffff0000, v2
	v_lshlrev_b32_e32 v54, 16, v3
	v_and_b32_e32 v55, 0xffff0000, v3
	v_lshlrev_b32_e32 v56, 16, v4
	v_and_b32_e32 v57, 0xffff0000, v4
	v_lshlrev_b32_e32 v58, 16, v5
	v_and_b32_e32 v59, 0xffff0000, v5
	v_lshlrev_b32_e32 v60, 16, v6
	v_and_b32_e32 v61, 0xffff0000, v6
	v_lshlrev_b32_e32 v62, 16, v7
	v_and_b32_e32 v63, 0xffff0000, v7
	v_lshlrev_b32_e32 v64, 16, v8
	v_and_b32_e32 v65, 0xffff0000, v8
	v_lshlrev_b32_e32 v66, 16, v9
	v_and_b32_e32 v67, 0xffff0000, v9
	v_lshlrev_b32_e32 v68, 16, v10
	v_and_b32_e32 v69, 0xffff0000, v10
	v_lshlrev_b32_e32 v70, 16, v11
	v_and_b32_e32 v71, 0xffff0000, v11
	v_lshlrev_b32_e32 v72, 16, v12
	v_and_b32_e32 v73, 0xffff0000, v12
	v_lshlrev_b32_e32 v74, 16, v13
	v_and_b32_e32 v75, 0xffff0000, v13
	v_lshlrev_b32_e32 v76, 16, v14
	v_and_b32_e32 v77, 0xffff0000, v14
	v_lshlrev_b32_e32 v78, 16, v15
	v_and_b32_e32 v79, 0xffff0000, v15
	v_pk_mul_f32 v[16:17], v[48:49], v[48:49]
	v_pk_fma_f32 v[16:17], v[50:51], v[50:51], v[16:17]
	v_pk_fma_f32 v[16:17], v[52:53], v[52:53], v[16:17]
	v_pk_fma_f32 v[16:17], v[54:55], v[54:55], v[16:17]
	v_pk_fma_f32 v[16:17], v[56:57], v[56:57], v[16:17]
	v_pk_fma_f32 v[16:17], v[58:59], v[58:59], v[16:17]
	v_pk_fma_f32 v[16:17], v[60:61], v[60:61], v[16:17]
	v_pk_fma_f32 v[16:17], v[62:63], v[62:63], v[16:17]
	v_pk_mul_f32 v[18:19], v[64:65], v[64:65]
	v_pk_fma_f32 v[18:19], v[66:67], v[66:67], v[18:19]
	v_pk_fma_f32 v[18:19], v[68:69], v[68:69], v[18:19]
	v_pk_fma_f32 v[18:19], v[70:71], v[70:71], v[18:19]
	v_pk_fma_f32 v[18:19], v[72:73], v[72:73], v[18:19]
	v_pk_fma_f32 v[18:19], v[74:75], v[74:75], v[18:19]
	v_pk_fma_f32 v[18:19], v[76:77], v[76:77], v[18:19]
	v_pk_fma_f32 v[18:19], v[78:79], v[78:79], v[18:19]
	v_add_f32_e32 v16, v16, v17
	v_add_f32_e32 v18, v18, v19
	s_nop 1
	v_add_f32_dpp v16, v16, v16 quad_perm:[1,0,3,2] row_mask:0xf bank_mask:0xf
	v_add_f32_dpp v18, v18, v18 quad_perm:[1,0,3,2] row_mask:0xf bank_mask:0xf
	s_nop 0
	v_add_f32_dpp v16, v16, v16 quad_perm:[2,3,0,1] row_mask:0xf bank_mask:0xf
	v_add_f32_dpp v18, v18, v18 quad_perm:[2,3,0,1] row_mask:0xf bank_mask:0xf
	s_nop 0
	v_add_f32_dpp v16, v16, v16 row_half_mirror row_mask:0xf bank_mask:0xf
	v_add_f32_dpp v18, v18, v18 row_half_mirror row_mask:0xf bank_mask:0xf
	s_nop 0
	v_add_f32_dpp v16, v16, v16 row_mirror row_mask:0xf bank_mask:0xf
	v_add_f32_dpp v18, v18, v18 row_mirror row_mask:0xf bank_mask:0xf
	s_nop 0
	v_add_f32_dpp v16, v16, v16 row_bcast:15 row_mask:0xa bank_mask:0xf
	v_add_f32_dpp v18, v18, v18 row_bcast:15 row_mask:0xa bank_mask:0xf
	s_nop 0
	v_add_f32_dpp v16, v16, v16 row_bcast:31 row_mask:0xc bank_mask:0xf
	v_add_f32_dpp v18, v18, v18 row_bcast:31 row_mask:0xc bank_mask:0xf
	s_nop 0
	v_readlane_b32 s12, v16, 63
	s_nop 1
	v_mov_b32_e32 v20, s12
	v_readlane_b32 s12, v18, 63
	s_nop 1
	v_mov_b32_e32 v22, s12
	v_fmamk_f32 v20, v20, 0x3a800000, v168
	v_fmamk_f32 v22, v22, 0x3a800000, v168
	v_rsq_f32_e32 v20, v20
	v_rsq_f32_e32 v22, v22
	s_nop 0
	v_pk_mul_f32 v[48:49], v[20:21], v[48:49] op_sel_hi:[0,1]
	v_pk_mul_f32 v[50:51], v[20:21], v[50:51] op_sel_hi:[0,1]
	v_pk_mul_f32 v[52:53], v[20:21], v[52:53] op_sel_hi:[0,1]
	v_pk_mul_f32 v[54:55], v[20:21], v[54:55] op_sel_hi:[0,1]
	v_pk_mul_f32 v[56:57], v[20:21], v[56:57] op_sel_hi:[0,1]
	v_pk_mul_f32 v[58:59], v[20:21], v[58:59] op_sel_hi:[0,1]
	v_pk_mul_f32 v[60:61], v[20:21], v[60:61] op_sel_hi:[0,1]
	v_pk_mul_f32 v[62:63], v[20:21], v[62:63] op_sel_hi:[0,1]
	v_pk_mul_f32 v[64:65], v[22:23], v[64:65] op_sel_hi:[0,1]
	v_pk_mul_f32 v[66:67], v[22:23], v[66:67] op_sel_hi:[0,1]
	v_pk_mul_f32 v[68:69], v[22:23], v[68:69] op_sel_hi:[0,1]
	v_pk_mul_f32 v[70:71], v[22:23], v[70:71] op_sel_hi:[0,1]
	v_pk_mul_f32 v[72:73], v[22:23], v[72:73] op_sel_hi:[0,1]
	v_pk_mul_f32 v[74:75], v[22:23], v[74:75] op_sel_hi:[0,1]
	v_pk_mul_f32 v[76:77], v[22:23], v[76:77] op_sel_hi:[0,1]
	v_pk_mul_f32 v[78:79], v[22:23], v[78:79] op_sel_hi:[0,1]
	s_waitcnt vmcnt(0)
	v_pk_fma_f32 v[88:89], v[48:49], v[120:121], v[88:89]
	v_pk_fma_f32 v[90:91], v[50:51], v[122:123], v[90:91]
	global_store_dwordx4 v80, v[88:91], s[36:37] offset:0 nt
	v_pk_fma_f32 v[92:93], v[52:53], v[124:125], v[92:93]
	v_pk_fma_f32 v[94:95], v[54:55], v[126:127], v[94:95]
	global_store_dwordx4 v80, v[92:95], s[36:37] offset:1024 nt
	v_pk_fma_f32 v[96:97], v[56:57], v[128:129], v[96:97]
	v_pk_fma_f32 v[98:99], v[58:59], v[130:131], v[98:99]
	global_store_dwordx4 v80, v[96:99], s[36:37] offset:2048 nt
	v_pk_fma_f32 v[100:101], v[60:61], v[132:133], v[100:101]
	v_pk_fma_f32 v[102:103], v[62:63], v[134:135], v[102:103]
	global_store_dwordx4 v80, v[100:103], s[36:37] offset:3072 nt
	v_pk_fma_f32 v[104:105], v[64:65], v[120:121], v[104:105]
	v_pk_fma_f32 v[106:107], v[66:67], v[122:123], v[106:107]
	global_store_dwordx4 v86, v[104:107], s[36:37] offset:0 nt
	v_pk_fma_f32 v[108:109], v[68:69], v[124:125], v[108:109]
	v_pk_fma_f32 v[110:111], v[70:71], v[126:127], v[110:111]
	global_store_dwordx4 v86, v[108:111], s[36:37] offset:1024 nt
	v_pk_fma_f32 v[112:113], v[72:73], v[128:129], v[112:113]
	v_pk_fma_f32 v[114:115], v[74:75], v[130:131], v[114:115]
	global_store_dwordx4 v86, v[112:115], s[36:37] offset:2048 nt
	v_pk_fma_f32 v[116:117], v[76:77], v[132:133], v[116:117]
	v_pk_fma_f32 v[118:119], v[78:79], v[134:135], v[118:119]
	global_store_dwordx4 v86, v[116:119], s[36:37] offset:3072 nt
	s_andn2_b64 vcc, exec, s[0:1]
	s_cbranch_vccnz .LBB0_400
; DI unsigned pk2(float lo, float hi) { f32x2 v = {lo, hi}; bf16x2_t b = __builtin_convertvector(v, bf16x2_t); return __builtin_bit_cast(unsigned, b); }
; DI void rowpass(const float* hsrc, const bf16_t* mix, const float* gpost, const float* gnext, float* hdst, bf16_t* hb, int gw, int NGW, int lane) {
;     ...
;         if (gnext) {
;             float ss[2] = {0.f, 0.f};
; #pragma unroll
;             for (int r = 0; r < 2; ++r)
; #pragma unroll
;                 for (int j = 0; j < 4; ++j) ss[r] += (hv[r][j].x * hv[r][j].x + hv[r][j].y * hv[r][j].y) + (hv[r][j].z * hv[r][j].z + hv[r][j].w * hv[r][j].w);
; #pragma unroll
;             for (int o = 1; o < 64; o <<= 1) { ss[0] += __shfl_xor(ss[0], o); ss[1] += __shfl_xor(ss[1], o); }
; #pragma unroll
;             for (int r = 0; r < 2; ++r) { const float rs = __builtin_amdgcn_rsqf(ss[r] * (1.0f / D) + EPS);
; #pragma unroll
;                 for (int j = 0; j < 4; ++j) { const f32x4 gn = *(const f32x4*)(gnext + 256 * j + 4 * lane); const f32x4 o = hv[r][j] * rs * gn;
;                     u32x2 w; w.x = pk2(o.x, o.y); w.y = pk2(o.z, o.w); *(u32x2*)(hb + (size_t)(m0 + r) * D + 256 * j + 4 * lane) = w; } }
	v_pk_mul_f32 v[16:17], v[88:89], v[88:89]
	v_pk_fma_f32 v[16:17], v[90:91], v[90:91], v[16:17]
	v_pk_fma_f32 v[16:17], v[92:93], v[92:93], v[16:17]
	v_pk_fma_f32 v[16:17], v[94:95], v[94:95], v[16:17]
	v_pk_fma_f32 v[16:17], v[96:97], v[96:97], v[16:17]
	v_pk_fma_f32 v[16:17], v[98:99], v[98:99], v[16:17]
	v_pk_fma_f32 v[16:17], v[100:101], v[100:101], v[16:17]
	v_pk_fma_f32 v[16:17], v[102:103], v[102:103], v[16:17]
	v_pk_mul_f32 v[18:19], v[104:105], v[104:105]
	v_pk_fma_f32 v[18:19], v[106:107], v[106:107], v[18:19]
	v_pk_fma_f32 v[18:19], v[108:109], v[108:109], v[18:19]
	v_pk_fma_f32 v[18:19], v[110:111], v[110:111], v[18:19]
	v_pk_fma_f32 v[18:19], v[112:113], v[112:113], v[18:19]
	v_pk_fma_f32 v[18:19], v[114:115], v[114:115], v[18:19]
	v_pk_fma_f32 v[18:19], v[116:117], v[116:117], v[18:19]
	v_pk_fma_f32 v[18:19], v[118:119], v[118:119], v[18:19]
	v_add_f32_e32 v16, v16, v17
	v_add_f32_e32 v18, v18, v19
	s_nop 1
	v_add_f32_dpp v16, v16, v16 quad_perm:[1,0,3,2] row_mask:0xf bank_mask:0xf
	v_add_f32_dpp v18, v18, v18 quad_perm:[1,0,3,2] row_mask:0xf bank_mask:0xf
	s_nop 0
	v_add_f32_dpp v16, v16, v16 quad_perm:[2,3,0,1] row_mask:0xf bank_mask:0xf
	v_add_f32_dpp v18, v18, v18 quad_perm:[2,3,0,1] row_mask:0xf bank_mask:0xf
	s_nop 0
	v_add_f32_dpp v16, v16, v16 row_half_mirror row_mask:0xf bank_mask:0xf
	v_add_f32_dpp v18, v18, v18 row_half_mirror row_mask:0xf bank_mask:0xf
	s_nop 0
	v_add_f32_dpp v16, v16, v16 row_mirror row_mask:0xf bank_mask:0xf
	v_add_f32_dpp v18, v18, v18 row_mirror row_mask:0xf bank_mask:0xf
	s_nop 0
	v_add_f32_dpp v16, v16, v16 row_bcast:15 row_mask:0xa bank_mask:0xf
	v_add_f32_dpp v18, v18, v18 row_bcast:15 row_mask:0xa bank_mask:0xf
	s_nop 0
	v_add_f32_dpp v16, v16, v16 row_bcast:31 row_mask:0xc bank_mask:0xf
	v_add_f32_dpp v18, v18, v18 row_bcast:31 row_mask:0xc bank_mask:0xf
	s_nop 0
	v_readlane_b32 s12, v16, 63
	s_nop 1
	v_mov_b32_e32 v20, s12
	v_readlane_b32 s12, v18, 63
	s_nop 1
	v_mov_b32_e32 v22, s12
	v_fmamk_f32 v20, v20, 0x3a800000, v168
	v_fmamk_f32 v22, v22, 0x3a800000, v168
	v_rsq_f32_e32 v20, v20
	v_rsq_f32_e32 v22, v22
	v_add_co_u32_e32 v82, vcc, 0xf2000000, v36
	s_nop 1
	v_addc_co_u32_e32 v83, vcc, -1, v37, vcc
	v_pk_mul_f32 v[48:49], v[88:89], v[20:21] op_sel_hi:[1,0]
	v_pk_mul_f32 v[50:51], v[90:91], v[20:21] op_sel_hi:[1,0]
	v_pk_mul_f32 v[48:49], v[48:49], v[176:177]
	v_pk_mul_f32 v[50:51], v[50:51], v[178:179]
	v_cvt_pk_bf16_f32 v0, v48, v49
	v_cvt_pk_bf16_f32 v1, v50, v51
	global_store_dwordx2 v[82:83], v[0:1], off offset:0
	v_pk_mul_f32 v[52:53], v[92:93], v[20:21] op_sel_hi:[1,0]
	v_pk_mul_f32 v[54:55], v[94:95], v[20:21] op_sel_hi:[1,0]
	v_pk_mul_f32 v[52:53], v[52:53], v[180:181]
	v_pk_mul_f32 v[54:55], v[54:55], v[182:183]
	v_cvt_pk_bf16_f32 v2, v52, v53
	v_cvt_pk_bf16_f32 v3, v54, v55
	global_store_dwordx2 v[82:83], v[2:3], off offset:512
	v_pk_mul_f32 v[56:57], v[96:97], v[20:21] op_sel_hi:[1,0]
	v_pk_mul_f32 v[58:59], v[98:99], v[20:21] op_sel_hi:[1,0]
	v_pk_mul_f32 v[56:57], v[56:57], v[184:185]
	v_pk_mul_f32 v[58:59], v[58:59], v[186:187]
	v_cvt_pk_bf16_f32 v4, v56, v57
	v_cvt_pk_bf16_f32 v5, v58, v59
	global_store_dwordx2 v[82:83], v[4:5], off offset:1024
	v_pk_mul_f32 v[60:61], v[100:101], v[20:21] op_sel_hi:[1,0]
	v_pk_mul_f32 v[62:63], v[102:103], v[20:21] op_sel_hi:[1,0]
	v_pk_mul_f32 v[60:61], v[60:61], v[188:189]
	v_pk_mul_f32 v[62:63], v[62:63], v[190:191]
	v_cvt_pk_bf16_f32 v6, v60, v61
	v_cvt_pk_bf16_f32 v7, v62, v63
	global_store_dwordx2 v[82:83], v[6:7], off offset:1536
	v_pk_mul_f32 v[64:65], v[104:105], v[22:23] op_sel_hi:[1,0]
	v_pk_mul_f32 v[66:67], v[106:107], v[22:23] op_sel_hi:[1,0]
	v_pk_mul_f32 v[64:65], v[64:65], v[176:177]
	v_pk_mul_f32 v[66:67], v[66:67], v[178:179]
	v_cvt_pk_bf16_f32 v8, v64, v65
	v_cvt_pk_bf16_f32 v9, v66, v67
	global_store_dwordx2 v[82:83], v[8:9], off offset:2048
	v_pk_mul_f32 v[68:69], v[108:109], v[22:23] op_sel_hi:[1,0]
	v_pk_mul_f32 v[70:71], v[110:111], v[22:23] op_sel_hi:[1,0]
	v_pk_mul_f32 v[68:69], v[68:69], v[180:181]
	v_pk_mul_f32 v[70:71], v[70:71], v[182:183]
	v_cvt_pk_bf16_f32 v10, v68, v69
	v_cvt_pk_bf16_f32 v11, v70, v71
	global_store_dwordx2 v[82:83], v[10:11], off offset:2560
	v_pk_mul_f32 v[72:73], v[112:113], v[22:23] op_sel_hi:[1,0]
	v_pk_mul_f32 v[74:75], v[114:115], v[22:23] op_sel_hi:[1,0]
	v_pk_mul_f32 v[72:73], v[72:73], v[184:185]
	v_pk_mul_f32 v[74:75], v[74:75], v[186:187]
	v_cvt_pk_bf16_f32 v12, v72, v73
	v_cvt_pk_bf16_f32 v13, v74, v75
	global_store_dwordx2 v[82:83], v[12:13], off offset:3072
	v_pk_mul_f32 v[76:77], v[116:117], v[22:23] op_sel_hi:[1,0]
	v_pk_mul_f32 v[78:79], v[118:119], v[22:23] op_sel_hi:[1,0]
	v_pk_mul_f32 v[76:77], v[76:77], v[188:189]
	v_pk_mul_f32 v[78:79], v[78:79], v[190:191]
	v_cvt_pk_bf16_f32 v14, v76, v77
	v_cvt_pk_bf16_f32 v15, v78, v79
	global_store_dwordx2 v[82:83], v[14:15], off offset:3584
	s_branch .LBB0_400
